# v25 plus pipelined G_out residual epilogue and G_up epilogue without redundant canonicalizing max
# baseline (speedup 1.0000x reference)
;     __device__ __forceinline__ void operator()(const f32x4 (&acc)[2][2][4][2], const Unit& u, int wr, int wc, int fr, int fq) const {
;     ...
;             for (int m = 0; m < 4; ++m) { const size_t off = (size_t)(rt0 + ai * HALF + wr * 64 + m * 16 + fr) * 1024 + col0;
; #pragma unroll
;                 for (int bj = 0; bj < 2; ++bj)
; #pragma unroll
;                     for (int n = 0; n < 2; ++n) {
;                         if (u.nt) {
;                             *(f32x4*)(out + (size_t)(u.k0 / (u.nt * BK)) * (512 * 1024) + off + bj * HALF + n * 16) = gv[bj][n] * acc[ai][bj][m][n]; }
;                         else { const f32x4 bs = *(const f32x4*)(base + off + bj * HALF + n * 16);
;                             *(f32x4*)(out + off + bj * HALF + n * 16) = bs + gv[bj][n] * acc[ai][bj][m][n]; } }
.Lepi_out_lat:
	v_lshl_add_u64 v[158:159], s[24:25], 0, v[158:159]
	s_mov_b64 s[4:5], 0x10000
	s_mov_b64 s[6:7], 0x50000
	global_load_dwordx4 v[166:169], v[158:159], off
	global_load_dwordx4 v[170:173], v[158:159], off offset:64
	global_load_dwordx4 v[174:177], v[158:159], off offset:512
	global_load_dwordx4 v[178:181], v[158:159], off offset:576
	v_lshl_add_u64 v[158:159], v[158:159], 0, s[4:5]
	global_load_dwordx4 v[182:185], v[158:159], off
	global_load_dwordx4 v[186:189], v[158:159], off offset:64
	global_load_dwordx4 v[190:193], v[158:159], off offset:512
	global_load_dwordx4 v[194:197], v[158:159], off offset:576
	v_lshl_add_u64 v[158:159], v[158:159], 0, s[4:5]
	global_load_dwordx4 v[198:201], v[158:159], off
	global_load_dwordx4 v[202:205], v[158:159], off offset:64
	s_waitcnt vmcnt(9)
	v_pk_fma_f32 v[144:145], v[144:145], v[80:81], v[168:169]
	v_pk_fma_f32 v[142:143], v[142:143], v[78:79], v[166:167]
	global_store_dwordx4 v[156:157], v[142:145], off
	global_load_dwordx4 v[166:169], v[158:159], off offset:512
	s_waitcnt vmcnt(10)
	v_pk_fma_f32 v[140:141], v[140:141], v[72:73], v[172:173]
	v_pk_fma_f32 v[138:139], v[138:139], v[70:71], v[170:171]
	global_store_dwordx4 v[156:157], v[138:141], off offset:64
	global_load_dwordx4 v[170:173], v[158:159], off offset:576
	v_lshl_add_u64 v[158:159], v[158:159], 0, s[4:5]
	s_waitcnt vmcnt(11)
	v_pk_fma_f32 v[136:137], v[136:137], v[64:65], v[176:177]
	v_pk_fma_f32 v[134:135], v[134:135], v[62:63], v[174:175]
	global_store_dwordx4 v[156:157], v[134:137], off offset:512
	global_load_dwordx4 v[174:177], v[158:159], off
	s_waitcnt vmcnt(12)
	v_pk_fma_f32 v[132:133], v[132:133], v[56:57], v[180:181]
	v_pk_fma_f32 v[130:131], v[130:131], v[54:55], v[178:179]
	global_store_dwordx4 v[156:157], v[130:133], off offset:576
	v_lshl_add_u64 v[156:157], v[156:157], 0, s[4:5]
	global_load_dwordx4 v[178:181], v[158:159], off offset:64
	s_waitcnt vmcnt(13)
	v_pk_fma_f32 v[128:129], v[128:129], v[80:81], v[184:185]
	v_pk_fma_f32 v[126:127], v[126:127], v[78:79], v[182:183]
	global_store_dwordx4 v[156:157], v[126:129], off
	global_load_dwordx4 v[182:185], v[158:159], off offset:512
	s_waitcnt vmcnt(14)
	v_pk_fma_f32 v[124:125], v[124:125], v[72:73], v[188:189]
	v_pk_fma_f32 v[122:123], v[122:123], v[70:71], v[186:187]
	global_store_dwordx4 v[156:157], v[122:125], off offset:64
	global_load_dwordx4 v[186:189], v[158:159], off offset:576
	v_lshl_add_u64 v[158:159], v[158:159], 0, s[6:7]
	s_waitcnt vmcnt(15)
	v_pk_fma_f32 v[120:121], v[120:121], v[64:65], v[192:193]
	v_pk_fma_f32 v[118:119], v[118:119], v[62:63], v[190:191]
	global_store_dwordx4 v[156:157], v[118:121], off offset:512
	global_load_dwordx4 v[190:193], v[158:159], off
	s_waitcnt vmcnt(16)
	v_pk_fma_f32 v[116:117], v[116:117], v[56:57], v[196:197]
	v_pk_fma_f32 v[114:115], v[114:115], v[54:55], v[194:195]
	global_store_dwordx4 v[156:157], v[114:117], off offset:576
	v_lshl_add_u64 v[156:157], v[156:157], 0, s[4:5]
	global_load_dwordx4 v[194:197], v[158:159], off offset:64
	s_waitcnt vmcnt(17)
	v_pk_fma_f32 v[112:113], v[112:113], v[80:81], v[200:201]
	v_pk_fma_f32 v[110:111], v[110:111], v[78:79], v[198:199]
	global_store_dwordx4 v[156:157], v[110:113], off
	global_load_dwordx4 v[198:201], v[158:159], off offset:512
	s_waitcnt vmcnt(18)
	v_pk_fma_f32 v[108:109], v[108:109], v[72:73], v[204:205]
	v_pk_fma_f32 v[106:107], v[106:107], v[70:71], v[202:203]
	global_store_dwordx4 v[156:157], v[106:109], off offset:64
	global_load_dwordx4 v[202:205], v[158:159], off offset:576
	v_lshl_add_u64 v[158:159], v[158:159], 0, s[4:5]
	s_waitcnt vmcnt(18)
	v_pk_fma_f32 v[104:105], v[104:105], v[64:65], v[168:169]
	v_pk_fma_f32 v[102:103], v[102:103], v[62:63], v[166:167]
	global_store_dwordx4 v[156:157], v[102:105], off offset:512
	global_load_dwordx4 v[166:169], v[158:159], off
	s_waitcnt vmcnt(18)
	v_pk_fma_f32 v[100:101], v[100:101], v[56:57], v[172:173]
	v_pk_fma_f32 v[98:99], v[98:99], v[54:55], v[170:171]
	global_store_dwordx4 v[156:157], v[98:101], off offset:576
	v_lshl_add_u64 v[156:157], v[156:157], 0, s[4:5]
	global_load_dwordx4 v[170:173], v[158:159], off offset:64
	s_waitcnt vmcnt(18)
	v_pk_fma_f32 v[96:97], v[96:97], v[80:81], v[176:177]
	v_pk_fma_f32 v[94:95], v[94:95], v[78:79], v[174:175]
	global_store_dwordx4 v[156:157], v[94:97], off
	global_load_dwordx4 v[174:177], v[158:159], off offset:512
	s_waitcnt vmcnt(18)
;     __device__ __forceinline__ void operator()(const f32x4 (&acc)[2][2][4][2], const Unit& u, int wr, int wc, int fr, int fq) const {
;     ...
;             for (int m = 0; m < 4; ++m) { const size_t off = (size_t)(rt0 + ai * HALF + wr * 64 + m * 16 + fr) * 1024 + col0;
; #pragma unroll
;                 for (int bj = 0; bj < 2; ++bj)
; #pragma unroll
;                     for (int n = 0; n < 2; ++n) {
;                         if (u.nt) {
;                             *(f32x4*)(out + (size_t)(u.k0 / (u.nt * BK)) * (512 * 1024) + off + bj * HALF + n * 16) = gv[bj][n] * acc[ai][bj][m][n]; }
;                         else { const f32x4 bs = *(const f32x4*)(base + off + bj * HALF + n * 16);
;                             *(f32x4*)(out + off + bj * HALF + n * 16) = bs + gv[bj][n] * acc[ai][bj][m][n]; } }
;                 if (m & 1) asm volatile("" ::: "memory"); }
	v_pk_fma_f32 v[92:93], v[92:93], v[72:73], v[180:181]
	v_pk_fma_f32 v[90:91], v[90:91], v[70:71], v[178:179]
	global_store_dwordx4 v[156:157], v[90:93], off offset:64
	global_load_dwordx4 v[178:181], v[158:159], off offset:576
	v_lshl_add_u64 v[158:159], v[158:159], 0, s[4:5]
	s_waitcnt vmcnt(18)
	v_pk_fma_f32 v[88:89], v[88:89], v[64:65], v[184:185]
	v_pk_fma_f32 v[86:87], v[86:87], v[62:63], v[182:183]
	global_store_dwordx4 v[156:157], v[86:89], off offset:512
	global_load_dwordx4 v[182:185], v[158:159], off
	s_waitcnt vmcnt(18)
	v_pk_fma_f32 v[84:85], v[84:85], v[56:57], v[188:189]
	v_pk_fma_f32 v[82:83], v[82:83], v[54:55], v[186:187]
	global_store_dwordx4 v[156:157], v[82:85], off offset:576
	v_lshl_add_u64 v[156:157], v[156:157], 0, s[6:7]
	global_load_dwordx4 v[186:189], v[158:159], off offset:64
	s_waitcnt vmcnt(18)
	v_pk_fma_f32 v[76:77], v[76:77], v[80:81], v[192:193]
	v_pk_fma_f32 v[74:75], v[74:75], v[78:79], v[190:191]
	global_store_dwordx4 v[156:157], v[74:77], off
	global_load_dwordx4 v[190:193], v[158:159], off offset:512
	s_waitcnt vmcnt(18)
	v_pk_fma_f32 v[68:69], v[68:69], v[72:73], v[196:197]
	v_pk_fma_f32 v[66:67], v[66:67], v[70:71], v[194:195]
	global_store_dwordx4 v[156:157], v[66:69], off offset:64
	global_load_dwordx4 v[194:197], v[158:159], off offset:576
	v_lshl_add_u64 v[158:159], v[158:159], 0, s[4:5]
	s_waitcnt vmcnt(18)
	v_pk_fma_f32 v[60:61], v[60:61], v[64:65], v[200:201]
	v_pk_fma_f32 v[58:59], v[58:59], v[62:63], v[198:199]
	global_store_dwordx4 v[156:157], v[58:61], off offset:512
	global_load_dwordx4 v[198:201], v[158:159], off
	s_waitcnt vmcnt(18)
	v_pk_fma_f32 v[52:53], v[52:53], v[56:57], v[204:205]
	v_pk_fma_f32 v[50:51], v[50:51], v[54:55], v[202:203]
	global_store_dwordx4 v[156:157], v[50:53], off offset:576
	v_lshl_add_u64 v[156:157], v[156:157], 0, s[4:5]
	global_load_dwordx4 v[202:205], v[158:159], off offset:64
	s_waitcnt vmcnt(18)
	v_pk_fma_f32 v[48:49], v[48:49], v[80:81], v[168:169]
	v_pk_fma_f32 v[46:47], v[46:47], v[78:79], v[166:167]
	global_store_dwordx4 v[156:157], v[46:49], off
	global_load_dwordx4 v[166:169], v[158:159], off offset:512
	s_waitcnt vmcnt(18)
	v_pk_fma_f32 v[44:45], v[44:45], v[72:73], v[172:173]
	v_pk_fma_f32 v[42:43], v[42:43], v[70:71], v[170:171]
	global_store_dwordx4 v[156:157], v[42:45], off offset:64
	global_load_dwordx4 v[170:173], v[158:159], off offset:576
	s_waitcnt vmcnt(18)
	v_pk_fma_f32 v[40:41], v[40:41], v[64:65], v[176:177]
	v_pk_fma_f32 v[38:39], v[38:39], v[62:63], v[174:175]
	global_store_dwordx4 v[156:157], v[38:41], off offset:512
	s_waitcnt vmcnt(17)
	v_pk_fma_f32 v[36:37], v[36:37], v[56:57], v[180:181]
	v_pk_fma_f32 v[34:35], v[34:35], v[54:55], v[178:179]
	global_store_dwordx4 v[156:157], v[34:37], off offset:576
	v_lshl_add_u64 v[156:157], v[156:157], 0, s[4:5]
	s_waitcnt vmcnt(16)
	v_pk_fma_f32 v[32:33], v[32:33], v[80:81], v[184:185]
	v_pk_fma_f32 v[30:31], v[30:31], v[78:79], v[182:183]
	global_store_dwordx4 v[156:157], v[30:33], off
	s_waitcnt vmcnt(15)
	v_pk_fma_f32 v[28:29], v[28:29], v[72:73], v[188:189]
	v_pk_fma_f32 v[26:27], v[26:27], v[70:71], v[186:187]
	global_store_dwordx4 v[156:157], v[26:29], off offset:64
	s_waitcnt vmcnt(14)
	v_pk_fma_f32 v[24:25], v[24:25], v[64:65], v[192:193]
	v_pk_fma_f32 v[22:23], v[22:23], v[62:63], v[190:191]
	global_store_dwordx4 v[156:157], v[22:25], off offset:512
	s_waitcnt vmcnt(13)
	v_pk_fma_f32 v[20:21], v[20:21], v[56:57], v[196:197]
	v_pk_fma_f32 v[18:19], v[18:19], v[54:55], v[194:195]
	global_store_dwordx4 v[156:157], v[18:21], off offset:576
	v_lshl_add_u64 v[156:157], v[156:157], 0, s[4:5]
	s_waitcnt vmcnt(12)
	v_pk_fma_f32 v[16:17], v[16:17], v[80:81], v[200:201]
	v_pk_fma_f32 v[14:15], v[14:15], v[78:79], v[198:199]
	global_store_dwordx4 v[156:157], v[14:17], off
	s_waitcnt vmcnt(11)
	v_pk_fma_f32 v[12:13], v[12:13], v[72:73], v[204:205]
	v_pk_fma_f32 v[10:11], v[10:11], v[70:71], v[202:203]
	global_store_dwordx4 v[156:157], v[10:13], off offset:64
	s_waitcnt vmcnt(10)
	v_pk_fma_f32 v[8:9], v[8:9], v[64:65], v[168:169]
	v_pk_fma_f32 v[6:7], v[6:7], v[62:63], v[166:167]
	global_store_dwordx4 v[156:157], v[6:9], off offset:512
	s_waitcnt vmcnt(9)
	v_pk_fma_f32 v[4:5], v[4:5], v[56:57], v[172:173]
	v_pk_fma_f32 v[2:3], v[2:3], v[54:55], v[170:171]
	global_store_dwordx4 v[156:157], v[2:5], off offset:576
	s_branch .LBB0_899

; __device__ __forceinline__ unsigned cvt_pk_bf16(float lo, float hi) { unsigned r; asm volatile("v_cvt_pk_bf16_f32 %0, %1, %2" : "=v"(r) : "v"(lo), "v"(hi)); return r; }
;     __device__ __forceinline__ void operator()(const f32x4 (&acc)[2][2][4][2], const Unit& u, int wr, int wc, int fr, int fq) const {
;         const int row0 = u.pm * BM + wr * 64 + fr; const int col0 = u.pn * BM + wc * 32 + 8 * fq;
; #pragma unroll
;         for (int ai = 0; ai < 2; ++ai)
; #pragma unroll
;             for (int m = 0; m < 4; ++m) { bf16_t* rowp = O + (size_t)(row0 + ai * HALF + m * 16) * ldc + col0;
; #pragma unroll
;                 for (int bj = 0; bj < 2; ++bj) { f32x4 v0 = acc[ai][bj][m][0], v1 = acc[ai][bj][m][1];
;                     if (ACT == 2) {
; #pragma unroll
;                         for (int q = 0; q < 4; ++q) { float a = fmaxf(v0[q], 0.f), b = fmaxf(v1[q], 0.f); v0[q] = a * a; v1[q] = b * b; } }
;                     u32x4 w; w.x = cvt_pk_bf16(v0[0], v0[1]); w.y = cvt_pk_bf16(v0[2], v0[3]); w.z = cvt_pk_bf16(v1[0], v1[1]); w.w = cvt_pk_bf16(v1[2], v1[3]);
;                     if (ACT == 2) __builtin_nontemporal_store(w, (u32x4*)(rowp + bj * HALF)); else *(u32x4*)(rowp + bj * HALF) = w; } }
.LBB0_1029:
	v_lshl_add_u32 v146, s44, 8, v142
	v_ashrrev_i32_e32 v147, 31, v146
	v_max_f32_e32 v122, 0, v122
	v_lshl_or_b32 v140, s4, 8, v144
	v_lshlrev_b64 v[148:149], 13, v[146:147]
	v_mul_f32_e32 v147, v122, v122
	v_max_f32_e32 v123, 0, v123
	v_max_f32_e32 v124, 0, v124
	v_ashrrev_i32_e32 v141, 31, v140
	v_max_f32_e32 v122, 0, v127
	v_mul_f32_e32 v127, v123, v123
	v_max_f32_e32 v123, v128, v128
	v_mul_f32_e32 v128, v124, v124
	v_lshl_add_u64 v[148:149], s[24:25], 0, v[148:149]
	v_lshlrev_b64 v[150:151], 1, v[140:141]
	v_max_f32_e32 v126, 0, v126
	v_mul_f32_e32 v122, v122, v122
	v_max_f32_e32 v123, 0, v123
	v_max_f32_e32 v124, 0, v129
	v_max_f32_e32 v125, 0, v125
	v_lshl_add_u64 v[140:141], v[148:149], 0, v[150:151]
	v_mul_f32_e32 v126, v126, v126
	v_mul_f32_e32 v123, v123, v123
	v_mul_f32_e32 v124, v124, v124
	v_mul_f32_e32 v125, v125, v125
	v_cvt_pk_bf16_f32 v122, v126, v122
	v_max_f32_e32 v114, 0, v114
	v_cvt_pk_bf16_f32 v123, v123, v124
	v_cvt_pk_bf16_f32 v124, v147, v127
	v_cvt_pk_bf16_f32 v125, v128, v125
	global_store_dwordx4 v[140:141], v[122:125], off
	v_max_f32_e32 v115, 0, v115
	v_max_f32_e32 v116, 0, v116
	v_mul_f32_e32 v122, v114, v114
	v_max_f32_e32 v114, 0, v119
	v_mul_f32_e32 v119, v115, v115
	v_max_f32_e32 v115, v120, v120
	v_mul_f32_e32 v120, v116, v116
	v_max_f32_e32 v118, 0, v118
	v_mul_f32_e32 v114, v114, v114
	v_max_f32_e32 v115, 0, v115
	v_max_f32_e32 v116, 0, v121
	v_max_f32_e32 v117, 0, v117
	v_mul_f32_e32 v118, v118, v118
	v_mul_f32_e32 v115, v115, v115
	v_mul_f32_e32 v116, v116, v116
	v_mul_f32_e32 v117, v117, v117
	v_cvt_pk_bf16_f32 v114, v118, v114
	v_cvt_pk_bf16_f32 v115, v115, v116
	v_cvt_pk_bf16_f32 v116, v122, v119
	v_cvt_pk_bf16_f32 v117, v120, v117
	global_store_dwordx4 v[140:141], v[114:117], off offset:256
	s_nop 0
	v_max_f32_e32 v106, 0, v106
	v_or_b32_e32 v114, 16, v146
	v_ashrrev_i32_e32 v115, 31, v114
	v_mul_f32_e32 v116, v106, v106
	v_max_f32_e32 v107, 0, v107
	v_max_f32_e32 v108, 0, v108
	v_lshlrev_b64 v[114:115], 13, v[114:115]
	v_max_f32_e32 v106, 0, v111
	v_mul_f32_e32 v111, v107, v107
	v_max_f32_e32 v107, v112, v112
	v_mul_f32_e32 v112, v108, v108
	v_lshl_add_u64 v[114:115], s[24:25], 0, v[114:115]
	v_max_f32_e32 v110, 0, v110
	v_mul_f32_e32 v106, v106, v106
	v_max_f32_e32 v107, 0, v107
	v_max_f32_e32 v108, 0, v113
	v_max_f32_e32 v109, 0, v109
	v_lshl_add_u64 v[114:115], v[114:115], 0, v[150:151]
	v_mul_f32_e32 v110, v110, v110
	v_mul_f32_e32 v107, v107, v107
	v_mul_f32_e32 v108, v108, v108
	v_mul_f32_e32 v109, v109, v109
	v_cvt_pk_bf16_f32 v106, v110, v106
	v_max_f32_e32 v98, 0, v98
	v_cvt_pk_bf16_f32 v107, v107, v108
	v_cvt_pk_bf16_f32 v108, v116, v111
	v_cvt_pk_bf16_f32 v109, v112, v109
	global_store_dwordx4 v[114:115], v[106:109], off
	v_max_f32_e32 v99, 0, v99
	v_max_f32_e32 v100, 0, v100
	v_mul_f32_e32 v106, v98, v98
	v_max_f32_e32 v98, 0, v103
	v_mul_f32_e32 v103, v99, v99
	v_max_f32_e32 v99, v104, v104
	v_mul_f32_e32 v104, v100, v100
	v_max_f32_e32 v102, 0, v102
	v_mul_f32_e32 v98, v98, v98
	v_max_f32_e32 v99, 0, v99
	v_max_f32_e32 v100, 0, v105
	v_max_f32_e32 v101, 0, v101
	v_mul_f32_e32 v102, v102, v102
	v_mul_f32_e32 v99, v99, v99
	v_mul_f32_e32 v100, v100, v100
	v_mul_f32_e32 v101, v101, v101
	v_cvt_pk_bf16_f32 v98, v102, v98
	v_cvt_pk_bf16_f32 v99, v99, v100
	v_cvt_pk_bf16_f32 v100, v106, v103
	v_cvt_pk_bf16_f32 v101, v104, v101
	global_store_dwordx4 v[114:115], v[98:101], off offset:256
	s_nop 0
	v_max_f32_e32 v90, 0, v90
	v_or_b32_e32 v98, 32, v146
	v_ashrrev_i32_e32 v99, 31, v98
	v_mul_f32_e32 v100, v90, v90
	v_max_f32_e32 v91, 0, v91
	v_max_f32_e32 v92, 0, v92
	v_lshlrev_b64 v[98:99], 13, v[98:99]
	v_max_f32_e32 v90, 0, v95
	v_mul_f32_e32 v95, v91, v91
	v_max_f32_e32 v91, v96, v96
	v_mul_f32_e32 v96, v92, v92
	v_lshl_add_u64 v[98:99], s[24:25], 0, v[98:99]
	v_max_f32_e32 v94, 0, v94
	v_mul_f32_e32 v90, v90, v90
	v_max_f32_e32 v91, 0, v91
	v_max_f32_e32 v92, 0, v97
	v_max_f32_e32 v93, 0, v93
	v_lshl_add_u64 v[98:99], v[98:99], 0, v[150:151]
	v_mul_f32_e32 v94, v94, v94
	v_mul_f32_e32 v91, v91, v91
	v_mul_f32_e32 v92, v92, v92
	v_mul_f32_e32 v93, v93, v93
	v_cvt_pk_bf16_f32 v90, v94, v90
	v_max_f32_e32 v82, 0, v82
	v_cvt_pk_bf16_f32 v91, v91, v92
	v_cvt_pk_bf16_f32 v92, v100, v95
	v_cvt_pk_bf16_f32 v93, v96, v93
	global_store_dwordx4 v[98:99], v[90:93], off
	v_max_f32_e32 v83, 0, v83
	v_max_f32_e32 v84, 0, v84
	v_mul_f32_e32 v90, v82, v82
	v_max_f32_e32 v82, 0, v87
	v_mul_f32_e32 v87, v83, v83
	v_max_f32_e32 v83, v88, v88
	v_mul_f32_e32 v88, v84, v84
	v_max_f32_e32 v86, 0, v86
	v_mul_f32_e32 v82, v82, v82
	v_max_f32_e32 v83, 0, v83
	v_max_f32_e32 v84, 0, v89
	v_max_f32_e32 v85, 0, v85
	v_mul_f32_e32 v86, v86, v86
	v_mul_f32_e32 v83, v83, v83
	v_mul_f32_e32 v84, v84, v84
	v_mul_f32_e32 v85, v85, v85
	v_cvt_pk_bf16_f32 v82, v86, v82
	v_cvt_pk_bf16_f32 v83, v83, v84
	v_cvt_pk_bf16_f32 v84, v90, v87
	v_cvt_pk_bf16_f32 v85, v88, v85
	global_store_dwordx4 v[98:99], v[82:85], off offset:256
	s_nop 0
	v_max_f32_e32 v74, 0, v74
	v_or_b32_e32 v82, 48, v146
	v_ashrrev_i32_e32 v83, 31, v82
	v_mul_f32_e32 v84, v74, v74
	v_max_f32_e32 v75, 0, v75
	v_max_f32_e32 v76, 0, v76
	v_lshlrev_b64 v[82:83], 13, v[82:83]
	v_max_f32_e32 v74, 0, v79
	v_mul_f32_e32 v79, v75, v75
	v_max_f32_e32 v75, v80, v80
	v_mul_f32_e32 v80, v76, v76
	v_lshl_add_u64 v[82:83], s[24:25], 0, v[82:83]
	v_max_f32_e32 v78, 0, v78
	v_mul_f32_e32 v74, v74, v74
	v_max_f32_e32 v75, 0, v75
	v_max_f32_e32 v76, 0, v81
	v_max_f32_e32 v77, 0, v77
	v_lshl_add_u64 v[82:83], v[82:83], 0, v[150:151]
	v_mul_f32_e32 v78, v78, v78
	v_mul_f32_e32 v75, v75, v75
	v_mul_f32_e32 v76, v76, v76
	v_mul_f32_e32 v77, v77, v77
	v_cvt_pk_bf16_f32 v74, v78, v74
; __device__ __forceinline__ unsigned cvt_pk_bf16(float lo, float hi) { unsigned r; asm volatile("v_cvt_pk_bf16_f32 %0, %1, %2" : "=v"(r) : "v"(lo), "v"(hi)); return r; }
;     __device__ __forceinline__ void operator()(const f32x4 (&acc)[2][2][4][2], const Unit& u, int wr, int wc, int fr, int fq) const {
;         const int row0 = u.pm * BM + wr * 64 + fr; const int col0 = u.pn * BM + wc * 32 + 8 * fq;
; #pragma unroll
;         for (int ai = 0; ai < 2; ++ai)
; #pragma unroll
;             for (int m = 0; m < 4; ++m) { bf16_t* rowp = O + (size_t)(row0 + ai * HALF + m * 16) * ldc + col0;
; #pragma unroll
;                 for (int bj = 0; bj < 2; ++bj) { f32x4 v0 = acc[ai][bj][m][0], v1 = acc[ai][bj][m][1];
;                     if (ACT == 2) {
; #pragma unroll
;                         for (int q = 0; q < 4; ++q) { float a = fmaxf(v0[q], 0.f), b = fmaxf(v1[q], 0.f); v0[q] = a * a; v1[q] = b * b; } }
;                     u32x4 w; w.x = cvt_pk_bf16(v0[0], v0[1]); w.y = cvt_pk_bf16(v0[2], v0[3]); w.z = cvt_pk_bf16(v1[0], v1[1]); w.w = cvt_pk_bf16(v1[2], v1[3]);
;                     if (ACT == 2) __builtin_nontemporal_store(w, (u32x4*)(rowp + bj * HALF)); else *(u32x4*)(rowp + bj * HALF) = w; } }
	v_max_f32_e32 v66, 0, v66
	v_max_f32_e32 v67, 0, v67
	v_max_f32_e32 v68, 0, v68
	v_cvt_pk_bf16_f32 v75, v75, v76
	v_cvt_pk_bf16_f32 v76, v84, v79
	v_cvt_pk_bf16_f32 v77, v80, v77
	global_store_dwordx4 v[82:83], v[74:77], off
	s_nop 1
	v_mul_f32_e32 v74, v66, v66
	v_max_f32_e32 v66, v71, v71
	v_mul_f32_e32 v71, v67, v67
	v_max_f32_e32 v67, v72, v72
	v_mul_f32_e32 v72, v68, v68
	v_max_f32_e32 v66, 0, v66
	v_max_f32_e32 v67, 0, v67
	v_max_f32_e32 v68, 0, v73
	v_max_f32_e32 v70, 0, v70
	v_mul_f32_e32 v66, v66, v66
	v_mul_f32_e32 v67, v67, v67
	v_max_f32_e32 v69, 0, v69
	v_mul_f32_e32 v68, v68, v68
	v_mul_f32_e32 v70, v70, v70
	v_mul_f32_e32 v69, v69, v69
	v_cvt_pk_bf16_f32 v66, v70, v66
	v_cvt_pk_bf16_f32 v67, v67, v68
	v_cvt_pk_bf16_f32 v68, v74, v71
	v_max_f32_e32 v58, 0, v58
	v_cvt_pk_bf16_f32 v69, v72, v69
	global_store_dwordx4 v[82:83], v[66:69], off offset:256
	s_nop 0
	v_max_f32_e32 v59, 0, v59
	v_mul_f32_e32 v68, v58, v58
	v_max_f32_e32 v60, 0, v60
	s_mov_b64 s[4:5], 0x100000
	v_max_f32_e32 v62, 0, v62
	v_max_f32_e32 v58, 0, v63
	v_mul_f32_e32 v63, v59, v59
	v_max_f32_e32 v59, v64, v64
	v_mul_f32_e32 v64, v60, v60
	v_lshl_add_u64 v[66:67], v[140:141], 0, s[4:5]
	v_mul_f32_e32 v62, v62, v62
	v_mul_f32_e32 v58, v58, v58
	v_max_f32_e32 v59, 0, v59
	v_max_f32_e32 v60, 0, v65
	s_mov_b32 s4, 0x100000
	v_mul_f32_e32 v59, v59, v59
	v_max_f32_e32 v61, 0, v61
	v_mul_f32_e32 v60, v60, v60
	v_cvt_pk_bf16_f32 v58, v62, v58
	v_add_co_u32_e32 v62, vcc, s4, v140
	v_mul_f32_e32 v61, v61, v61
	v_cvt_pk_bf16_f32 v59, v59, v60
	v_cvt_pk_bf16_f32 v60, v68, v63
	v_addc_co_u32_e32 v63, vcc, 0, v141, vcc
	v_max_f32_e32 v50, 0, v50
	v_max_f32_e32 v51, 0, v51
	v_max_f32_e32 v52, 0, v52
	v_cvt_pk_bf16_f32 v61, v64, v61
	global_store_dwordx4 v[62:63], v[58:61], off
	s_nop 1
	v_mul_f32_e32 v58, v50, v50
	v_max_f32_e32 v50, v55, v55
	v_mul_f32_e32 v55, v51, v51
	v_max_f32_e32 v51, v56, v56
	v_mul_f32_e32 v56, v52, v52
	v_max_f32_e32 v50, 0, v50
	v_max_f32_e32 v51, 0, v51
	v_max_f32_e32 v52, 0, v57
	v_max_f32_e32 v54, 0, v54
	v_mul_f32_e32 v50, v50, v50
	v_mul_f32_e32 v51, v51, v51
	v_max_f32_e32 v53, 0, v53
	v_mul_f32_e32 v52, v52, v52
	v_mul_f32_e32 v54, v54, v54
	v_mul_f32_e32 v53, v53, v53
	v_cvt_pk_bf16_f32 v50, v54, v50
	v_cvt_pk_bf16_f32 v51, v51, v52
	v_cvt_pk_bf16_f32 v52, v58, v55
	v_max_f32_e32 v42, 0, v42
	v_cvt_pk_bf16_f32 v53, v56, v53
	global_store_dwordx4 v[66:67], v[50:53], off offset:256
	s_nop 0
	v_max_f32_e32 v43, 0, v43
	v_mul_f32_e32 v52, v42, v42
	v_max_f32_e32 v44, 0, v44
	s_mov_b64 s[4:5], 0x120000
	v_max_f32_e32 v46, 0, v46
	v_max_f32_e32 v42, 0, v47
	v_mul_f32_e32 v47, v43, v43
	v_max_f32_e32 v43, v48, v48
	v_mul_f32_e32 v48, v44, v44
	v_lshl_add_u64 v[50:51], v[140:141], 0, s[4:5]
	v_mul_f32_e32 v46, v46, v46
	v_mul_f32_e32 v42, v42, v42
	v_max_f32_e32 v43, 0, v43
	v_max_f32_e32 v44, 0, v49
	s_mov_b32 s4, 0x120000
	v_mul_f32_e32 v43, v43, v43
	v_max_f32_e32 v45, 0, v45
	v_mul_f32_e32 v44, v44, v44
	v_cvt_pk_bf16_f32 v42, v46, v42
	v_add_co_u32_e32 v46, vcc, s4, v140
	v_mul_f32_e32 v45, v45, v45
	v_cvt_pk_bf16_f32 v43, v43, v44
	v_cvt_pk_bf16_f32 v44, v52, v47
	v_addc_co_u32_e32 v47, vcc, 0, v141, vcc
	v_max_f32_e32 v34, 0, v34
	v_max_f32_e32 v35, 0, v35
	v_max_f32_e32 v36, 0, v36
	v_cvt_pk_bf16_f32 v45, v48, v45
	global_store_dwordx4 v[46:47], v[42:45], off
	s_nop 1
	v_mul_f32_e32 v42, v34, v34
	v_max_f32_e32 v34, v39, v39
	v_mul_f32_e32 v39, v35, v35
	v_max_f32_e32 v35, v40, v40
	v_mul_f32_e32 v40, v36, v36
	v_max_f32_e32 v34, 0, v34
	v_max_f32_e32 v35, 0, v35
	v_max_f32_e32 v36, 0, v41
	v_max_f32_e32 v38, 0, v38
; __device__ __forceinline__ unsigned cvt_pk_bf16(float lo, float hi) { unsigned r; asm volatile("v_cvt_pk_bf16_f32 %0, %1, %2" : "=v"(r) : "v"(lo), "v"(hi)); return r; }
; #define PG8_BAR __builtin_amdgcn_s_barrier()
;     __device__ __forceinline__ void operator()(const f32x4 (&acc)[2][2][4][2], const Unit& u, int wr, int wc, int fr, int fq) const {
;         const int row0 = u.pm * BM + wr * 64 + fr; const int col0 = u.pn * BM + wc * 32 + 8 * fq;
; #pragma unroll
;         for (int ai = 0; ai < 2; ++ai)
; #pragma unroll
;             for (int m = 0; m < 4; ++m) { bf16_t* rowp = O + (size_t)(row0 + ai * HALF + m * 16) * ldc + col0;
; #pragma unroll
;                 for (int bj = 0; bj < 2; ++bj) { f32x4 v0 = acc[ai][bj][m][0], v1 = acc[ai][bj][m][1];
;                     if (ACT == 2) {
; #pragma unroll
;                         for (int q = 0; q < 4; ++q) { float a = fmaxf(v0[q], 0.f), b = fmaxf(v1[q], 0.f); v0[q] = a * a; v1[q] = b * b; } }
;                     u32x4 w; w.x = cvt_pk_bf16(v0[0], v0[1]); w.y = cvt_pk_bf16(v0[2], v0[3]); w.z = cvt_pk_bf16(v1[0], v1[1]); w.w = cvt_pk_bf16(v1[2], v1[3]);
;                     if (ACT == 2) __builtin_nontemporal_store(w, (u32x4*)(rowp + bj * HALF)); else *(u32x4*)(rowp + bj * HALF) = w; } }
; template <class Epi, class Sched, bool ALIGN_EPI = false, bool SP2 = false>
; __device__ __forceinline__ void gemm_phase(PG8_LAS unsigned char* lds, const Gemm g, const Sched& S, const Epi& E) {
;     ...
;         if constexpr (ALIGN_EPI) { if (wr == 0) PG8_BAR; }
;         if constexpr (!Epi::AFTER_DRAIN) { E(acc, cur, wr, wc, fr, fq); S.done(cur); }
;         if (!has_next) break;
; #pragma unroll
;         for (int a = 0; a < 2; ++a)
; #pragma unroll
;             for (int b = 0; b < 2; ++b)
; #pragma unroll
;                 for (int m = 0; m < 4; ++m)
; #pragma unroll
;                     for (int n = 0; n < 2; ++n) acc[a][b][m][n] = (f32x4){0.f, 0.f, 0.f, 0.f};
;         cur = nxt; cA = nA; cB = nB; ++ui;
;         if constexpr (ALIGN_EPI) { if (wr == 1) PG8_BAR; }
	v_mul_f32_e32 v34, v34, v34
	v_mul_f32_e32 v35, v35, v35
	v_max_f32_e32 v37, 0, v37
	v_mul_f32_e32 v36, v36, v36
	v_mul_f32_e32 v38, v38, v38
	v_mul_f32_e32 v37, v37, v37
	v_cvt_pk_bf16_f32 v34, v38, v34
	v_cvt_pk_bf16_f32 v35, v35, v36
	v_cvt_pk_bf16_f32 v36, v42, v39
	v_max_f32_e32 v26, 0, v26
	v_cvt_pk_bf16_f32 v37, v40, v37
	global_store_dwordx4 v[50:51], v[34:37], off offset:256
	s_nop 0
	v_max_f32_e32 v27, 0, v27
	v_mul_f32_e32 v36, v26, v26
	v_max_f32_e32 v28, 0, v28
	s_mov_b64 s[4:5], 0x140000
	v_max_f32_e32 v30, 0, v30
	v_max_f32_e32 v26, 0, v31
	v_mul_f32_e32 v31, v27, v27
	v_max_f32_e32 v27, v32, v32
	v_mul_f32_e32 v32, v28, v28
	v_lshl_add_u64 v[34:35], v[140:141], 0, s[4:5]
	v_mul_f32_e32 v30, v30, v30
	v_mul_f32_e32 v26, v26, v26
	v_max_f32_e32 v27, 0, v27
	v_max_f32_e32 v28, 0, v33
	s_mov_b32 s4, 0x140000
	v_mul_f32_e32 v27, v27, v27
	v_max_f32_e32 v29, 0, v29
	v_mul_f32_e32 v28, v28, v28
	v_cvt_pk_bf16_f32 v26, v30, v26
	v_add_co_u32_e32 v30, vcc, s4, v140
	v_mul_f32_e32 v29, v29, v29
	v_cvt_pk_bf16_f32 v27, v27, v28
	v_cvt_pk_bf16_f32 v28, v36, v31
	v_addc_co_u32_e32 v31, vcc, 0, v141, vcc
	v_max_f32_e32 v18, 0, v18
	v_max_f32_e32 v19, 0, v19
	v_max_f32_e32 v20, 0, v20
	v_cvt_pk_bf16_f32 v29, v32, v29
	global_store_dwordx4 v[30:31], v[26:29], off
	s_nop 1
	v_mul_f32_e32 v26, v18, v18
	v_max_f32_e32 v18, v23, v23
	v_mul_f32_e32 v23, v19, v19
	v_max_f32_e32 v19, v24, v24
	v_mul_f32_e32 v24, v20, v20
	v_max_f32_e32 v18, 0, v18
	v_max_f32_e32 v19, 0, v19
	v_max_f32_e32 v20, 0, v25
	v_max_f32_e32 v22, 0, v22
	v_mul_f32_e32 v18, v18, v18
	v_mul_f32_e32 v19, v19, v19
	v_max_f32_e32 v21, 0, v21
	v_mul_f32_e32 v20, v20, v20
	v_mul_f32_e32 v22, v22, v22
	v_mul_f32_e32 v21, v21, v21
	v_cvt_pk_bf16_f32 v18, v22, v18
	v_cvt_pk_bf16_f32 v19, v19, v20
	v_cvt_pk_bf16_f32 v20, v26, v23
	v_max_f32_e32 v10, 0, v10
	v_cvt_pk_bf16_f32 v21, v24, v21
	global_store_dwordx4 v[34:35], v[18:21], off offset:256
	s_nop 0
	v_max_f32_e32 v11, 0, v11
	v_mul_f32_e32 v20, v10, v10
	v_max_f32_e32 v12, 0, v12
	s_mov_b64 s[4:5], 0x160000
	v_max_f32_e32 v14, 0, v14
	v_max_f32_e32 v10, 0, v15
	v_mul_f32_e32 v15, v11, v11
	v_max_f32_e32 v11, v16, v16
	v_mul_f32_e32 v16, v12, v12
	v_lshl_add_u64 v[18:19], v[140:141], 0, s[4:5]
	v_mul_f32_e32 v14, v14, v14
	v_mul_f32_e32 v10, v10, v10
	v_max_f32_e32 v11, 0, v11
	v_max_f32_e32 v12, 0, v17
	s_mov_b32 s4, 0x160000
	v_mul_f32_e32 v11, v11, v11
	v_max_f32_e32 v13, 0, v13
	v_mul_f32_e32 v12, v12, v12
	v_cvt_pk_bf16_f32 v10, v14, v10
	v_add_co_u32_e32 v14, vcc, s4, v140
	v_mul_f32_e32 v13, v13, v13
	v_cvt_pk_bf16_f32 v11, v11, v12
	v_cvt_pk_bf16_f32 v12, v20, v15
	v_addc_co_u32_e32 v15, vcc, 0, v141, vcc
	v_max_f32_e32 v2, 0, v2
	v_max_f32_e32 v3, 0, v3
	v_max_f32_e32 v4, 0, v4
	v_cvt_pk_bf16_f32 v13, v16, v13
	global_store_dwordx4 v[14:15], v[10:13], off
	s_nop 1
	v_mul_f32_e32 v10, v2, v2
	v_max_f32_e32 v2, v7, v7
	v_mul_f32_e32 v7, v3, v3
	v_max_f32_e32 v3, v8, v8
	v_mul_f32_e32 v8, v4, v4
	v_max_f32_e32 v2, 0, v2
	v_max_f32_e32 v3, 0, v3
	v_max_f32_e32 v4, 0, v9
	v_max_f32_e32 v5, 0, v5
	v_max_f32_e32 v6, 0, v6
	v_mul_f32_e32 v2, v2, v2
	v_mul_f32_e32 v3, v3, v3
	v_mul_f32_e32 v4, v4, v4
	v_mul_f32_e32 v5, v5, v5
	s_andn2_b64 vcc, exec, s[38:39]
	s_mov_b64 s[38:39], -1
	v_mul_f32_e32 v6, v6, v6
	v_cvt_pk_bf16_f32 v2, v6, v2
	v_cvt_pk_bf16_f32 v3, v3, v4
	v_cvt_pk_bf16_f32 v4, v10, v7
	v_cvt_pk_bf16_f32 v5, v8, v5
	global_store_dwordx4 v[18:19], v[2:5], off offset:256
	s_cbranch_vccnz .LBB0_1022
	s_andn2_b64 vcc, exec, s[2:3]
	s_cbranch_vccnz .LBB0_1021
	s_barrier
	s_branch .LBB0_1021
